# v70 + first three K-fragment reads of each M segment issued before the preceding barrier
# speedup vs baseline: 1.0128x; 1.0128x over previous
; __device__ __forceinline__ int v_st(int k, int c) { const int kk = (k & ~0xC) | ((k & 4) << 1) | ((k & 8) >> 1); return ((kk >> 3) * 4 + (c >> 5)) * 512 + ((kk & 7) * 32 + (c & 31)) * 2; }
; __device__ __forceinline__ int v_rd_base(int lane) { return ((lane & 3) << 3) | (((lane >> 2) & 3) << 6) | (((lane >> 4) & 1) << 5) | (((lane >> 5) & 1) << 8); }
; __device__ __forceinline__ void attn_unit_pp(int b, int h, int qb, int par, const bf16_t* __restrict__ QBp, const bf16_t* __restrict__ KBp, const bf16_t* __restrict__ VBp, ...
;     ...
;   const float qposf = (float)(q0 + w4 * QBLK + r32 - 4 * hi);
;   const int sr = t256 >> 4, sc = (t256 & 15) * 8;
;   int woff[4];
; #pragma unroll
;   for (int i = 0; i < 4; ++i) { const int row = sr + 16 * i; woff[i] = g ? (int)(2 * SHM_V) + KSWZ(row, sc * 2) : v_st(row, sc); }
;   const bf16_t* Tsrc = (g ? Kh : Vh) + (long)sr * LD + sc;
;   const char* Kmine = K_lds + g * 128;
;   const int vb0 = (int)(uintptr_t)V_lds + v_rd_base(lane);
;   float m_reg = 0.f, l_reg = 0.f, alpha = 1.f; f32x16 o[4]; f32x16 negm = f32x16{}; f32x16 p0, p1; bf16x8 pa0, pa1, pa2, pa3; bf16x8 stg[4];
; #pragma unroll
;   for (int d = 0; d < 4; ++d) o[d] = f32x16{};
.LBB0_362:
	v_lshlrev_b32_e32 v3, 4, v186
	v_lshlrev_b32_e32 v188, 2, v6
	v_lshlrev_b32_e32 v2, 3, v186
	v_and_b32_e32 v3, 0xc0, v3
	v_lshlrev_b32_e32 v6, 1, v186
	v_and_or_b32 v3, v2, 24, v3
	v_and_b32_e32 v6, 32, v6
	v_and_b32_e32 v2, 0x100, v2
	v_or3_b32 v191, v3, v6, v2
	v_and_b32_e32 v2, 0x3fffffc0, v4
	v_lshl_add_u32 v2, v2, 2, s53
	s_mov_b32 s46, 0
	s_cmp_lt_i32 s11, 0
	v_cmp_gt_u32_e64 s[2:3], 32, v186
	v_lshl_add_u32 v190, v179, 2, v2
	v_lshl_add_u32 v189, v188, 2, v2
	s_cbranch_scc1 .LBB0_402
	v_sub_u32_e32 v2, v5, v188
	s_lshl_b32 s14, s38, 7
	v_lshlrev_b32_e32 v3, 4, v179
	s_add_i32 s16, s14, 0
	v_cvt_f32_i32_e32 v192, v2
	v_lshlrev_b32_e32 v2, 8, v179
	v_and_b32_e32 v3, 0x70, v3
	v_or_b32_e32 v4, 32, v0
	s_cmp_lg_u32 0, -1
	v_bitop3_b32 v20, v0, v2, v3 bitop3:0xde
	v_bitop3_b32 v21, v4, v2, v3 bitop3:0xde
	v_or_b32_e32 v4, 64, v0
	v_or_b32_e32 v0, 0x60, v0
	s_cselect_b32 s14, 0, 0
	v_bitop3_b32 v22, v4, v2, v3 bitop3:0xde
	v_bitop3_b32 v23, v0, v2, v3 bitop3:0xde
	v_mov_b32_e32 v14, v1
	v_mov_b32_e32 v15, v1
	v_add_u32_e32 v193, s14, v191
	s_addk_i32 s14, 0x4000
	s_add_i32 s38, s11, s17
	v_mov_b32_e32 v0, v1
	v_mov_b32_e32 v2, v1
	v_mov_b32_e32 v3, v1
	v_mov_b32_e32 v4, v1
	v_mov_b32_e32 v5, v1
	v_mov_b32_e32 v6, v1
	v_mov_b32_e32 v7, v1
	v_mov_b32_e32 v8, v1
	v_mov_b32_e32 v9, v1
	v_mov_b32_e32 v10, v1
	v_mov_b32_e32 v11, v1
	v_mov_b32_e32 v12, v1
	v_mov_b32_e32 v13, v1
	v_mov_b32_e32 v80, 0
	v_add_u32_e32 v195, s16, v20
	v_add_u32_e32 v196, s16, v21
	v_add_u32_e32 v197, s16, v22
	v_add_u32_e32 v198, s16, v23
	v_add_u32_e32 v199, 0, v17
	v_add_u32_e32 v200, 0, v18
	v_add_u32_e32 v201, 0, v19
	v_add_u32_e32 v202, 0, v16
	v_mov_b64_e32 v[78:79], v[14:15]
	v_mov_b64_e32 v[62:63], v[14:15]
	v_mov_b64_e32 v[46:47], v[14:15]
	v_mov_b64_e32 v[30:31], v[14:15]
	v_mov_b64_e32 v[96:97], v[14:15]
	v_add_u32_e32 v194, s14, v191
	v_mov_b32_e32 v172, 0xf149f2ca
	s_mov_b64 s[14:15], -1
	s_mov_b32 s39, s38
	v_mov_b64_e32 v[76:77], v[12:13]
	v_mov_b64_e32 v[74:75], v[10:11]
	v_mov_b64_e32 v[72:73], v[8:9]
	v_mov_b64_e32 v[70:71], v[6:7]
	v_mov_b64_e32 v[68:69], v[4:5]
	v_mov_b64_e32 v[66:67], v[2:3]
	v_mov_b64_e32 v[64:65], v[0:1]
	v_mov_b64_e32 v[60:61], v[12:13]
	v_mov_b64_e32 v[58:59], v[10:11]
	v_mov_b64_e32 v[56:57], v[8:9]
	v_mov_b64_e32 v[54:55], v[6:7]
	v_mov_b64_e32 v[52:53], v[4:5]
	v_mov_b64_e32 v[50:51], v[2:3]
	v_mov_b64_e32 v[48:49], v[0:1]
	v_mov_b64_e32 v[44:45], v[12:13]
	v_mov_b64_e32 v[42:43], v[10:11]
	v_mov_b64_e32 v[40:41], v[8:9]
	v_mov_b64_e32 v[38:39], v[6:7]
	v_mov_b64_e32 v[36:37], v[4:5]
	v_mov_b64_e32 v[34:35], v[2:3]
	v_mov_b64_e32 v[32:33], v[0:1]
	v_mov_b64_e32 v[28:29], v[12:13]
	v_mov_b64_e32 v[26:27], v[10:11]
	v_mov_b64_e32 v[24:25], v[8:9]
	v_mov_b64_e32 v[22:23], v[6:7]
	v_mov_b64_e32 v[20:21], v[4:5]
	v_mov_b64_e32 v[18:19], v[2:3]
	v_mov_b64_e32 v[16:17], v[0:1]
	v_mov_b64_e32 v[94:95], v[12:13]
	v_mov_b64_e32 v[92:93], v[10:11]
	v_mov_b64_e32 v[90:91], v[8:9]
	v_mov_b64_e32 v[88:89], v[6:7]
	v_mov_b64_e32 v[86:87], v[4:5]
	v_mov_b64_e32 v[84:85], v[2:3]
	v_mov_b64_e32 v[82:83], v[0:1]
	v_mov_b32_e32 v173, v80
	ds_read_b128 v[114:117], v195 offset:32768
	ds_read_b128 v[212:215], v195 offset:40960
	ds_read_b128 v[216:219], v196 offset:32768
; template <int D0> __device__ __forceinline__ void pv_one(f32x16& od, int vb, bf16x8 pa0, bf16x8 pa1, bf16x8 pa2, bf16x8 pa3) {
;   const s16x4 l0 = tr_read<v_rd_off(D0, 0, 0)>(vb), h0 = tr_read<v_rd_off(D0, 0, 1)>(vb), l1 = tr_read<v_rd_off(D0, 1, 0)>(vb), h1 = tr_read<v_rd_off(D0, 1, 1)>(vb);
;   const s16x4 l2 = tr_read<v_rd_off(D0, 2, 0)>(vb), h2 = tr_read<v_rd_off(D0, 2, 1)>(vb), l3 = tr_read<v_rd_off(D0, 3, 0)>(vb), h3 = tr_read<v_rd_off(D0, 3, 1)>(vb);
;   asm volatile("s_waitcnt lgkmcnt(0)" ::: "memory"); SBAR();
;     ...
;   od = __builtin_amdgcn_mfma_f32_32x32x16_bf16(pa0, PK(l0, h0), od, 0, 0, 0);
;   od = __builtin_amdgcn_mfma_f32_32x32x16_bf16(pa1, PK(l1, h1), od, 0, 0, 0);
;   od = __builtin_amdgcn_mfma_f32_32x32x16_bf16(pa2, PK(l2, h2), od, 0, 0, 0);
;   od = __builtin_amdgcn_mfma_f32_32x32x16_bf16(pa3, PK(l3, h3), od, 0, 0, 0);
;     ...
; }
; __device__ __forceinline__ void pv_d0(f32x16* o, int vb, bf16x8 pa0, bf16x8 pa1, bf16x8 pa2, bf16x8 pa3) {
;   pv_one<0>(o[0], vb, pa0, pa1, pa2, pa3); pv_one<1>(o[1], vb, pa0, pa1, pa2, pa3); pv_one<2>(o[2], vb, pa0, pa1, pa2, pa3); pv_one<3>(o[3], vb, pa0, pa1, pa2, pa3);
; }
; __device__ __forceinline__ void qkt_c(f32x16& p0, f32x16& p1, const char* Ks, const bf16x8* qr, const f32x16& negm, int r32, int hi) {
; #pragma unroll
;   for (int d0 = 0; d0 < 4; ++d0) { const int cb = (d0 * 16 + hi * 8) * 2;
;     bf16x8 b0 = *reinterpret_cast<const bf16x8*>(Ks + KSWZ(r32, cb));
;     bf16x8 b1 = *reinterpret_cast<const bf16x8*>(Ks + KSWZ(32 + r32, cb));
;     if (d0 == 0) { p0 = __builtin_amdgcn_mfma_f32_32x32x16_bf16(b0, qr[0], negm, 0, 0, 0); p1 = __builtin_amdgcn_mfma_f32_32x32x16_bf16(b1, qr[0], negm, 0, 0, 0); }
;     else { p0 = __builtin_amdgcn_mfma_f32_32x32x16_bf16(b0, qr[d0], p0, 0, 0, 0); p1 = __builtin_amdgcn_mfma_f32_32x32x16_bf16(b1, qr[d0], p1, 0, 0, 0); } }
; }
; template <int R> __device__ __forceinline__ void bias_r(f32x16& p0, f32x16& p1, float dq, float nslope) {
;   constexpr int C0 = (R & 3) + 8 * (R >> 2);
;   float x0, x1, a0 = p0[R], a1 = p1[R];
;   asm("v_sub_f32_e32 %0, %1, %2" : "=v"(x0) : "n"(__builtin_bit_cast(int, (float)C0)), "v"(dq));
;   asm("v_sub_f32_e32 %0, %1, %2" : "=v"(x1) : "n"(__builtin_bit_cast(int, (float)(C0 + 32))), "v"(dq));
;   asm("v_fma_f32 %0, %1, |%2|, %0" : "+v"(a0) : "v"(nslope), "v"(x0));
;   asm("v_fma_f32 %0, %1, |%2|, %0" : "+v"(a1) : "v"(nslope), "v"(x1));
.LBB0_364:
	s_and_b64 vcc, exec, s[14:15]
	s_waitcnt lgkmcnt(2)
	v_mfma_f32_32x32x16_bf16 v[98:113], v[114:117], v[130:133], v[82:97]
	ds_read_b128 v[220:223], v196 offset:40960
	s_waitcnt lgkmcnt(2)
	v_mfma_f32_32x32x16_bf16 v[114:129], v[212:215], v[130:133], v[82:97]
	ds_read_b128 v[212:215], v197 offset:32768
	s_waitcnt lgkmcnt(2)
	v_mfma_f32_32x32x16_bf16 v[98:113], v[216:219], v[134:137], v[98:113]
	ds_read_b128 v[216:219], v197 offset:40960
	s_waitcnt lgkmcnt(2)
	v_mfma_f32_32x32x16_bf16 v[114:129], v[220:223], v[134:137], v[114:129]
	ds_read_b128 v[220:223], v198 offset:32768
	s_waitcnt lgkmcnt(2)
	v_mfma_f32_32x32x16_bf16 v[98:113], v[212:215], v[138:141], v[98:113]
	ds_read_b128 v[212:215], v198 offset:40960
	s_waitcnt lgkmcnt(2)
	v_mfma_f32_32x32x16_bf16 v[114:129], v[216:219], v[138:141], v[114:129]
	s_cbranch_vccnz .Lqk_tail_0
	ds_read_b64_tr_b16 v[204:205], v194 offset:0
	ds_read_b64_tr_b16 v[206:207], v194 offset:0x800
	ds_read_b64_tr_b16 v[208:209], v194 offset:0x1000
	ds_read_b64_tr_b16 v[210:211], v194 offset:0x1800
	s_waitcnt lgkmcnt(5)
	v_mfma_f32_32x32x16_bf16 v[98:113], v[220:223], v[142:145], v[98:113]
	s_waitcnt lgkmcnt(4)
	v_mfma_f32_32x32x16_bf16 v[114:129], v[212:215], v[142:145], v[114:129]
	s_add_i32 s72, s22, s46
	s_cmp_lt_i32 s46, s23
	s_cselect_b32 s14, s72, s39
	s_lshl_b32 s14, s14, 6
	v_cvt_f32_i32_e32 v0, s14
	v_sub_f32_e32 v0, v192, v0
	ds_read_b64_tr_b16 v[212:213], v194 offset:0x2000
	ds_read_b64_tr_b16 v[214:215], v194 offset:0x2800
	ds_read_b64_tr_b16 v[216:217], v194 offset:0x3000
	ds_read_b64_tr_b16 v[218:219], v194 offset:0x3800
	s_waitcnt lgkmcnt(6)
	v_mfma_f32_32x32x16_bf16 v[64:79], v[2:5], v[204:207], v[64:79]
	v_sub_f32_e32 v14, 0, v0
	v_sub_f32_e32 v15, 0x42000000, v0
	v_fma_f32 v98, v81, |v14|, v98
	v_sub_f32_e32 v14, 0x3f800000, v0
	ds_read_b64_tr_b16 v[204:205], v194 offset:0x200
	ds_read_b64_tr_b16 v[206:207], v194 offset:0xa00
	s_waitcnt lgkmcnt(6)
	v_mfma_f32_32x32x16_bf16 v[64:79], v[6:9], v[208:211], v[64:79]
	v_fma_f32 v114, v81, |v15|, v114
	v_sub_f32_e32 v15, 0x42040000, v0
	v_fma_f32 v99, v81, |v14|, v99
	v_sub_f32_e32 v14, 0x40000000, v0
	ds_read_b64_tr_b16 v[208:209], v194 offset:0x1200
	ds_read_b64_tr_b16 v[210:211], v194 offset:0x1a00
	s_waitcnt lgkmcnt(6)
	v_mfma_f32_32x32x16_bf16 v[64:79], v[10:13], v[212:215], v[64:79]
	v_fma_f32 v115, v81, |v15|, v115
	v_sub_f32_e32 v15, 0x42080000, v0
	v_fma_f32 v100, v81, |v14|, v100
	v_sub_f32_e32 v14, 0x40400000, v0
	ds_read_b64_tr_b16 v[212:213], v194 offset:0x2200
	ds_read_b64_tr_b16 v[214:215], v194 offset:0x2a00
	ds_read_b64_tr_b16 v[220:221], v194 offset:0x3200
	ds_read_b64_tr_b16 v[222:223], v194 offset:0x3a00
	s_waitcnt lgkmcnt(8)
	v_mfma_f32_32x32x16_bf16 v[64:79], v[162:165], v[216:219], v[64:79]
	v_fma_f32 v116, v81, |v15|, v116
	v_sub_f32_e32 v15, 0x420c0000, v0
	v_fma_f32 v101, v81, |v14|, v101
	v_sub_f32_e32 v14, 0x41000000, v0
	s_waitcnt lgkmcnt(6)
	v_mfma_f32_32x32x16_bf16 v[48:63], v[2:5], v[204:207], v[48:63]
	v_fma_f32 v117, v81, |v15|, v117
	v_sub_f32_e32 v15, 0x42200000, v0
	v_fma_f32 v102, v81, |v14|, v102
	v_sub_f32_e32 v14, 0x41100000, v0
	ds_read_b64_tr_b16 v[204:205], v194 offset:0x400
	ds_read_b64_tr_b16 v[206:207], v194 offset:0xc00
	s_waitcnt lgkmcnt(6)
	v_mfma_f32_32x32x16_bf16 v[48:63], v[6:9], v[208:211], v[48:63]
	v_fma_f32 v118, v81, |v15|, v118
	v_sub_f32_e32 v15, 0x42240000, v0
	v_fma_f32 v103, v81, |v14|, v103
	v_sub_f32_e32 v14, 0x41200000, v0
	ds_read_b64_tr_b16 v[208:209], v194 offset:0x1400
	ds_read_b64_tr_b16 v[210:211], v194 offset:0x1c00
	s_waitcnt lgkmcnt(6)
	v_mfma_f32_32x32x16_bf16 v[48:63], v[10:13], v[212:215], v[48:63]
	v_fma_f32 v119, v81, |v15|, v119
	v_sub_f32_e32 v15, 0x42280000, v0
	v_fma_f32 v104, v81, |v14|, v104
	v_sub_f32_e32 v14, 0x41300000, v0
	ds_read_b64_tr_b16 v[212:213], v194 offset:0x2400
	ds_read_b64_tr_b16 v[214:215], v194 offset:0x2c00
	ds_read_b64_tr_b16 v[216:217], v194 offset:0x3400
	ds_read_b64_tr_b16 v[218:219], v194 offset:0x3c00
	s_waitcnt lgkmcnt(8)
	v_mfma_f32_32x32x16_bf16 v[48:63], v[162:165], v[220:223], v[48:63]
	v_fma_f32 v120, v81, |v15|, v120
	v_sub_f32_e32 v15, 0x422c0000, v0
	v_fma_f32 v105, v81, |v14|, v105
	v_sub_f32_e32 v14, 0x41800000, v0
	s_waitcnt lgkmcnt(6)
	v_mfma_f32_32x32x16_bf16 v[32:47], v[2:5], v[204:207], v[32:47]
	v_fma_f32 v121, v81, |v15|, v121
	v_sub_f32_e32 v15, 0x42400000, v0
	v_fma_f32 v106, v81, |v14|, v106
	v_sub_f32_e32 v14, 0x41880000, v0
	ds_read_b64_tr_b16 v[204:205], v194 offset:0x600
	ds_read_b64_tr_b16 v[206:207], v194 offset:0xe00
	s_waitcnt lgkmcnt(6)
	v_mfma_f32_32x32x16_bf16 v[32:47], v[6:9], v[208:211], v[32:47]
	v_fma_f32 v122, v81, |v15|, v122
	v_sub_f32_e32 v15, 0x42440000, v0
	v_fma_f32 v107, v81, |v14|, v107
	v_sub_f32_e32 v14, 0x41900000, v0
	ds_read_b64_tr_b16 v[208:209], v194 offset:0x1600
	ds_read_b64_tr_b16 v[210:211], v194 offset:0x1e00
	s_waitcnt lgkmcnt(6)
	v_mfma_f32_32x32x16_bf16 v[32:47], v[10:13], v[212:215], v[32:47]
	v_fma_f32 v123, v81, |v15|, v123
	v_sub_f32_e32 v15, 0x42480000, v0
	v_fma_f32 v108, v81, |v14|, v108
	v_sub_f32_e32 v14, 0x41980000, v0
	ds_read_b64_tr_b16 v[212:213], v194 offset:0x2600
	ds_read_b64_tr_b16 v[214:215], v194 offset:0x2e00
	ds_read_b64_tr_b16 v[220:221], v194 offset:0x3600
	ds_read_b64_tr_b16 v[222:223], v194 offset:0x3e00
	s_waitcnt lgkmcnt(8)
	v_mfma_f32_32x32x16_bf16 v[32:47], v[162:165], v[216:219], v[32:47]
	v_fma_f32 v124, v81, |v15|, v124
	v_sub_f32_e32 v15, 0x424c0000, v0
	v_fma_f32 v109, v81, |v14|, v109
	v_sub_f32_e32 v14, 0x41c00000, v0
	s_waitcnt lgkmcnt(6)
	v_mfma_f32_32x32x16_bf16 v[16:31], v[2:5], v[204:207], v[16:31]
	v_fma_f32 v125, v81, |v15|, v125
	v_sub_f32_e32 v15, 0x42600000, v0
	v_fma_f32 v110, v81, |v14|, v110
	v_sub_f32_e32 v14, 0x41c80000, v0
	s_waitcnt lgkmcnt(4)
	v_mfma_f32_32x32x16_bf16 v[16:31], v[6:9], v[208:211], v[16:31]
	v_fma_f32 v126, v81, |v15|, v126
	v_sub_f32_e32 v15, 0x42640000, v0
	v_fma_f32 v111, v81, |v14|, v111
	v_sub_f32_e32 v14, 0x41d00000, v0
	s_waitcnt lgkmcnt(2)
	v_mfma_f32_32x32x16_bf16 v[16:31], v[10:13], v[212:215], v[16:31]
	v_fma_f32 v127, v81, |v15|, v127
	v_sub_f32_e32 v15, 0x42680000, v0
	v_fma_f32 v112, v81, |v14|, v112
	v_sub_f32_e32 v14, 0x41d80000, v0
	s_waitcnt lgkmcnt(0)
	v_mfma_f32_32x32x16_bf16 v[16:31], v[162:165], v[220:223], v[16:31]
	v_sub_f32_e32 v0, 0x426c0000, v0
	v_fma_f32 v128, v81, |v15|, v128
	v_fma_f32 v113, v81, |v14|, v113
	v_fma_f32 v129, v81, |v0|, v129
	s_barrier
	s_branch .Lafter_bias_0

; template <int D0> __device__ __forceinline__ void pv_one(f32x16& od, int vb, bf16x8 pa0, bf16x8 pa1, bf16x8 pa2, bf16x8 pa3) {
;   const s16x4 l0 = tr_read<v_rd_off(D0, 0, 0)>(vb), h0 = tr_read<v_rd_off(D0, 0, 1)>(vb), l1 = tr_read<v_rd_off(D0, 1, 0)>(vb), h1 = tr_read<v_rd_off(D0, 1, 1)>(vb);
;   const s16x4 l2 = tr_read<v_rd_off(D0, 2, 0)>(vb), h2 = tr_read<v_rd_off(D0, 2, 1)>(vb), l3 = tr_read<v_rd_off(D0, 3, 0)>(vb), h3 = tr_read<v_rd_off(D0, 3, 1)>(vb);
;   asm volatile("s_waitcnt lgkmcnt(0)" ::: "memory"); SBAR();
;     ...
;   od = __builtin_amdgcn_mfma_f32_32x32x16_bf16(pa0, PK(l0, h0), od, 0, 0, 0);
;   od = __builtin_amdgcn_mfma_f32_32x32x16_bf16(pa1, PK(l1, h1), od, 0, 0, 0);
;   od = __builtin_amdgcn_mfma_f32_32x32x16_bf16(pa2, PK(l2, h2), od, 0, 0, 0);
;   od = __builtin_amdgcn_mfma_f32_32x32x16_bf16(pa3, PK(l3, h3), od, 0, 0, 0);
;     ...
; }
; __device__ __forceinline__ void pv_d0(f32x16* o, int vb, bf16x8 pa0, bf16x8 pa1, bf16x8 pa2, bf16x8 pa3) {
;   pv_one<0>(o[0], vb, pa0, pa1, pa2, pa3); pv_one<1>(o[1], vb, pa0, pa1, pa2, pa3); pv_one<2>(o[2], vb, pa0, pa1, pa2, pa3); pv_one<3>(o[3], vb, pa0, pa1, pa2, pa3);
; }
; __device__ __forceinline__ void qkt_c(f32x16& p0, f32x16& p1, const char* Ks, const bf16x8* qr, const f32x16& negm, int r32, int hi) {
; #pragma unroll
;   for (int d0 = 0; d0 < 4; ++d0) { const int cb = (d0 * 16 + hi * 8) * 2;
;     bf16x8 b0 = *reinterpret_cast<const bf16x8*>(Ks + KSWZ(r32, cb));
;     bf16x8 b1 = *reinterpret_cast<const bf16x8*>(Ks + KSWZ(32 + r32, cb));
;     if (d0 == 0) { p0 = __builtin_amdgcn_mfma_f32_32x32x16_bf16(b0, qr[0], negm, 0, 0, 0); p1 = __builtin_amdgcn_mfma_f32_32x32x16_bf16(b1, qr[0], negm, 0, 0, 0); }
;     else { p0 = __builtin_amdgcn_mfma_f32_32x32x16_bf16(b0, qr[d0], p0, 0, 0, 0); p1 = __builtin_amdgcn_mfma_f32_32x32x16_bf16(b1, qr[d0], p1, 0, 0, 0); } }
; }
; template <int R> __device__ __forceinline__ void bias_r(f32x16& p0, f32x16& p1, float dq, float nslope) {
;   constexpr int C0 = (R & 3) + 8 * (R >> 2);
;   float x0, x1, a0 = p0[R], a1 = p1[R];
;   asm("v_sub_f32_e32 %0, %1, %2" : "=v"(x0) : "n"(__builtin_bit_cast(int, (float)C0)), "v"(dq));
;   asm("v_sub_f32_e32 %0, %1, %2" : "=v"(x1) : "n"(__builtin_bit_cast(int, (float)(C0 + 32))), "v"(dq));
;   asm("v_fma_f32 %0, %1, |%2|, %0" : "+v"(a0) : "v"(nslope), "v"(x0));
;   asm("v_fma_f32 %0, %1, |%2|, %0" : "+v"(a1) : "v"(nslope), "v"(x1));
.LBB0_379:
	s_waitcnt lgkmcnt(0)
	ds_read_b128 v[114:117], v195 offset:49152
	ds_read_b128 v[212:215], v195 offset:57344
	ds_read_b128 v[216:219], v196 offset:49152
	s_barrier
	s_andn2_b64 vcc, exec, s[14:15]
	s_waitcnt lgkmcnt(2)
	v_mfma_f32_32x32x16_bf16 v[98:113], v[114:117], v[130:133], v[82:97]
	ds_read_b128 v[220:223], v196 offset:57344
	s_waitcnt lgkmcnt(2)
	v_mfma_f32_32x32x16_bf16 v[114:129], v[212:215], v[130:133], v[82:97]
	ds_read_b128 v[212:215], v197 offset:49152
	s_waitcnt lgkmcnt(2)
	v_mfma_f32_32x32x16_bf16 v[98:113], v[216:219], v[134:137], v[98:113]
	ds_read_b128 v[216:219], v197 offset:57344
	s_waitcnt lgkmcnt(2)
	v_mfma_f32_32x32x16_bf16 v[114:129], v[220:223], v[134:137], v[114:129]
	ds_read_b128 v[220:223], v198 offset:49152
	s_waitcnt lgkmcnt(2)
	v_mfma_f32_32x32x16_bf16 v[98:113], v[212:215], v[138:141], v[98:113]
	ds_read_b128 v[212:215], v198 offset:57344
	s_waitcnt lgkmcnt(2)
	v_mfma_f32_32x32x16_bf16 v[114:129], v[216:219], v[138:141], v[114:129]
	s_cbranch_vccnz .Lqk_tail_1
	ds_read_b64_tr_b16 v[204:205], v193 offset:0
	ds_read_b64_tr_b16 v[206:207], v193 offset:0x800
	ds_read_b64_tr_b16 v[208:209], v193 offset:0x1000
	ds_read_b64_tr_b16 v[210:211], v193 offset:0x1800
	s_waitcnt lgkmcnt(5)
	v_mfma_f32_32x32x16_bf16 v[98:113], v[220:223], v[142:145], v[98:113]
	s_waitcnt lgkmcnt(4)
	v_mfma_f32_32x32x16_bf16 v[114:129], v[212:215], v[142:145], v[114:129]
	s_add_i32 s46, s47, -1
	s_add_i32 s72, s72, 1
	s_add_i32 s14, s39, -1
	s_cmp_lt_i32 s46, s23
	s_cselect_b32 s14, s72, s14
	s_lshl_b32 s14, s14, 6
	v_cvt_f32_i32_e32 v0, s14
	v_sub_f32_e32 v0, v192, v0
	ds_read_b64_tr_b16 v[212:213], v193 offset:0x2000
	ds_read_b64_tr_b16 v[214:215], v193 offset:0x2800
	ds_read_b64_tr_b16 v[216:217], v193 offset:0x3000
	ds_read_b64_tr_b16 v[218:219], v193 offset:0x3800
	s_waitcnt lgkmcnt(6)
	v_mfma_f32_32x32x16_bf16 v[64:79], v[2:5], v[204:207], v[64:79]
	v_sub_f32_e32 v14, 0, v0
	v_sub_f32_e32 v15, 0x42000000, v0
	v_fma_f32 v98, v81, |v14|, v98
	v_sub_f32_e32 v14, 0x3f800000, v0
	ds_read_b64_tr_b16 v[204:205], v193 offset:0x200
	ds_read_b64_tr_b16 v[206:207], v193 offset:0xa00
	s_waitcnt lgkmcnt(6)
	v_mfma_f32_32x32x16_bf16 v[64:79], v[6:9], v[208:211], v[64:79]
	v_fma_f32 v114, v81, |v15|, v114
	v_sub_f32_e32 v15, 0x42040000, v0
	v_fma_f32 v99, v81, |v14|, v99
	v_sub_f32_e32 v14, 0x40000000, v0
	ds_read_b64_tr_b16 v[208:209], v193 offset:0x1200
	ds_read_b64_tr_b16 v[210:211], v193 offset:0x1a00
	s_waitcnt lgkmcnt(6)
	v_mfma_f32_32x32x16_bf16 v[64:79], v[10:13], v[212:215], v[64:79]
	v_fma_f32 v115, v81, |v15|, v115
	v_sub_f32_e32 v15, 0x42080000, v0
	v_fma_f32 v100, v81, |v14|, v100
	v_sub_f32_e32 v14, 0x40400000, v0
	ds_read_b64_tr_b16 v[212:213], v193 offset:0x2200
	ds_read_b64_tr_b16 v[214:215], v193 offset:0x2a00
	ds_read_b64_tr_b16 v[220:221], v193 offset:0x3200
	ds_read_b64_tr_b16 v[222:223], v193 offset:0x3a00
	s_waitcnt lgkmcnt(8)
	v_mfma_f32_32x32x16_bf16 v[64:79], v[162:165], v[216:219], v[64:79]
	v_fma_f32 v116, v81, |v15|, v116
	v_sub_f32_e32 v15, 0x420c0000, v0
	v_fma_f32 v101, v81, |v14|, v101
	v_sub_f32_e32 v14, 0x41000000, v0
	s_waitcnt lgkmcnt(6)
	v_mfma_f32_32x32x16_bf16 v[48:63], v[2:5], v[204:207], v[48:63]
	v_fma_f32 v117, v81, |v15|, v117
	v_sub_f32_e32 v15, 0x42200000, v0
	v_fma_f32 v102, v81, |v14|, v102
	v_sub_f32_e32 v14, 0x41100000, v0
	ds_read_b64_tr_b16 v[204:205], v193 offset:0x400
	ds_read_b64_tr_b16 v[206:207], v193 offset:0xc00
	s_waitcnt lgkmcnt(6)
	v_mfma_f32_32x32x16_bf16 v[48:63], v[6:9], v[208:211], v[48:63]
	v_fma_f32 v118, v81, |v15|, v118
	v_sub_f32_e32 v15, 0x42240000, v0
	v_fma_f32 v103, v81, |v14|, v103
	v_sub_f32_e32 v14, 0x41200000, v0
	ds_read_b64_tr_b16 v[208:209], v193 offset:0x1400
	ds_read_b64_tr_b16 v[210:211], v193 offset:0x1c00
	s_waitcnt lgkmcnt(6)
	v_mfma_f32_32x32x16_bf16 v[48:63], v[10:13], v[212:215], v[48:63]
	v_fma_f32 v119, v81, |v15|, v119
	v_sub_f32_e32 v15, 0x42280000, v0
	v_fma_f32 v104, v81, |v14|, v104
	v_sub_f32_e32 v14, 0x41300000, v0
	ds_read_b64_tr_b16 v[212:213], v193 offset:0x2400
	ds_read_b64_tr_b16 v[214:215], v193 offset:0x2c00
	ds_read_b64_tr_b16 v[216:217], v193 offset:0x3400
	ds_read_b64_tr_b16 v[218:219], v193 offset:0x3c00
	s_waitcnt lgkmcnt(8)
	v_mfma_f32_32x32x16_bf16 v[48:63], v[162:165], v[220:223], v[48:63]
	v_fma_f32 v120, v81, |v15|, v120
	v_sub_f32_e32 v15, 0x422c0000, v0
	v_fma_f32 v105, v81, |v14|, v105
	v_sub_f32_e32 v14, 0x41800000, v0
	s_waitcnt lgkmcnt(6)
	v_mfma_f32_32x32x16_bf16 v[32:47], v[2:5], v[204:207], v[32:47]
	v_fma_f32 v121, v81, |v15|, v121
	v_sub_f32_e32 v15, 0x42400000, v0
	v_fma_f32 v106, v81, |v14|, v106
	v_sub_f32_e32 v14, 0x41880000, v0
	ds_read_b64_tr_b16 v[204:205], v193 offset:0x600
	ds_read_b64_tr_b16 v[206:207], v193 offset:0xe00
	s_waitcnt lgkmcnt(6)
	v_mfma_f32_32x32x16_bf16 v[32:47], v[6:9], v[208:211], v[32:47]
	v_fma_f32 v122, v81, |v15|, v122
	v_sub_f32_e32 v15, 0x42440000, v0
	v_fma_f32 v107, v81, |v14|, v107
	v_sub_f32_e32 v14, 0x41900000, v0
	ds_read_b64_tr_b16 v[208:209], v193 offset:0x1600
	ds_read_b64_tr_b16 v[210:211], v193 offset:0x1e00
	s_waitcnt lgkmcnt(6)
	v_mfma_f32_32x32x16_bf16 v[32:47], v[10:13], v[212:215], v[32:47]
	v_fma_f32 v123, v81, |v15|, v123
	v_sub_f32_e32 v15, 0x42480000, v0
	v_fma_f32 v108, v81, |v14|, v108
	v_sub_f32_e32 v14, 0x41980000, v0
	ds_read_b64_tr_b16 v[212:213], v193 offset:0x2600
	ds_read_b64_tr_b16 v[214:215], v193 offset:0x2e00
	ds_read_b64_tr_b16 v[220:221], v193 offset:0x3600
	ds_read_b64_tr_b16 v[222:223], v193 offset:0x3e00
	s_waitcnt lgkmcnt(8)
	v_mfma_f32_32x32x16_bf16 v[32:47], v[162:165], v[216:219], v[32:47]
	v_fma_f32 v124, v81, |v15|, v124
	v_sub_f32_e32 v15, 0x424c0000, v0
	v_fma_f32 v109, v81, |v14|, v109
	v_sub_f32_e32 v14, 0x41c00000, v0
	s_waitcnt lgkmcnt(6)
	v_mfma_f32_32x32x16_bf16 v[16:31], v[2:5], v[204:207], v[16:31]
	v_fma_f32 v125, v81, |v15|, v125
	v_sub_f32_e32 v15, 0x42600000, v0
	v_fma_f32 v110, v81, |v14|, v110
	v_sub_f32_e32 v14, 0x41c80000, v0
	s_waitcnt lgkmcnt(4)
	v_mfma_f32_32x32x16_bf16 v[16:31], v[6:9], v[208:211], v[16:31]
	v_fma_f32 v126, v81, |v15|, v126
	v_sub_f32_e32 v15, 0x42640000, v0
	v_fma_f32 v111, v81, |v14|, v111
	v_sub_f32_e32 v14, 0x41d00000, v0
	s_waitcnt lgkmcnt(2)
	v_mfma_f32_32x32x16_bf16 v[16:31], v[10:13], v[212:215], v[16:31]
	v_fma_f32 v127, v81, |v15|, v127
	v_sub_f32_e32 v15, 0x42680000, v0
	v_fma_f32 v112, v81, |v14|, v112
	v_sub_f32_e32 v14, 0x41d80000, v0
	s_waitcnt lgkmcnt(0)
	v_mfma_f32_32x32x16_bf16 v[16:31], v[162:165], v[220:223], v[16:31]
	v_sub_f32_e32 v0, 0x426c0000, v0
	v_fma_f32 v128, v81, |v15|, v128
	v_fma_f32 v113, v81, |v14|, v113
	v_fma_f32 v129, v81, |v0|, v129
	s_barrier
	s_branch .Lafter_bias_1

; __device__ __forceinline__ void attn_unit_pp(int b, int h, int qb, int par, const bf16_t* __restrict__ QBp, const bf16_t* __restrict__ KBp, const bf16_t* __restrict__ VBp, ...
;     ...
;   _Pragma("nounroll") for (int j = 0; j < n; j += 2) { PP_STEP(j, 0); PP_STEP(j + 1, 1); }
.LBB0_393:
	s_xor_b64 s[14:15], s[14:15], -1
	s_add_i32 s39, s39, -2
	s_cmp_gt_i32 s47, s11
	s_waitcnt lgkmcnt(0)
	ds_read_b128 v[114:117], v195 offset:32768
	ds_read_b128 v[212:215], v195 offset:40960
	ds_read_b128 v[216:219], v196 offset:32768
	s_barrier
	s_cbranch_scc1 .LBB0_403
	s_mov_b32 s46, s47
	s_branch .LBB0_364
